# gate and pWpe GEMM phase ends: wait only for the trailing LDS-DMA loads (vmcnt 32/16) instead of draining the last epilogue stores before the next phase starts
# speedup vs baseline: 1.0082x; 1.0082x over previous
; #define PG8_WAIT_V(n) asm volatile("s_waitcnt vmcnt(" #n ")" ::: "memory")
; #define PG8_BAR __builtin_amdgcn_s_barrier()
;     ...
;     PG8_WAIT_V(0);
;     if constexpr (!ALIGN_EPI) { if (wr == 0) PG8_BAR; }
;     PG8_BAR;
.LBB0_740:
	s_waitcnt vmcnt(32)
	v_readlane_b32 s30, v255, 10
	v_readlane_b32 s31, v255, 11
	s_barrier

; #define PG8_WAIT_V(n) asm volatile("s_waitcnt vmcnt(" #n ")" ::: "memory")
; #define PG8_BAR __builtin_amdgcn_s_barrier()
;     ...
;     PG8_WAIT_V(0);
;     if constexpr (!ALIGN_EPI) { if (wr == 0) PG8_BAR; }
;     PG8_BAR;
.LBB0_765:
	s_waitcnt vmcnt(16)
	v_readlane_b32 s30, v255, 10
	v_readlane_b32 s31, v255, 11
	s_barrier
